# T12: softmax row-max cross-lane reductions via v_permlane16/32_swap instead of ds_bpermute (10 sites, phase 3 loop + A loop)
# speedup vs baseline: 1.0084x; 1.0084x over previous
; DI void gload2(R2& r, const bf16_t* gsrc, size_t gp, int tid) { r.a = ld_chunk(gsrc, gp, tid); r.b = ld_chunk(gsrc, gp, tid + 256); }
; DI void gload4(R4& r, const bf16_t* gsrc, size_t gp, int tid) { r.a = ld_chunk(gsrc, gp, tid); r.b = ld_chunk(gsrc, gp, tid + 256); r.c = ld_chunk(gsrc, gp, tid + 512); r.d = ld_chunk(gsrc, gp, tid + 768); }
; DI float softmax_step(f32x4 (&st)[4], float& m, float& lsum) {
;   float mx = fmaxf(fmaxf(fmaxf(st[0][0], st[0][1]), fmaxf(st[0][2], st[0][3])), fmaxf(fmaxf(st[1][0], st[1][1]), fmaxf(st[1][2], st[1][3])));
;   mx = fmaxf(mx, fmaxf(fmaxf(fmaxf(st[2][0], st[2][1]), fmaxf(st[2][2], st[2][3])), fmaxf(fmaxf(st[3][0], st[3][1]), fmaxf(st[3][2], st[3][3]))));
;   mx = fmaxf(mx, __shfl_xor(mx, 16)); mx = fmaxf(mx, __shfl_xor(mx, 32));
;   const float mn = fmaxf(m, mx);
;   const float mu = mn == -INFINITY ? 0.f : mn;
;   const float alpha = __builtin_amdgcn_exp2f(m - mu);
; DI void attn_A(const Params& P, int l, int b, int head, int qt, float lam, char* smem, bf16_t* ybase, size_t ypitch) {
;     ...
;     const char* sb = smem + (n & 1) * STAGE;
;     if (n < qt) {
;       const bf16_t* kn = kbase + (size_t)(n + 1) * 64 * PW;
;       gload2(rk0, kn, PW, tid); gload2(rk1, kn + 64, PW, tid); gload4(rv, vbase + (n + 1) * 64, SEQ, tid);
;     }
;     f32x4 s0[4], s1[4];
;     qk_tile(s0, sb, qf0, lr, g);
;     qk_tile(s1, sb + 9216, qf1, lr, g);
;     const float a0 = softmax_step(s0, m0, l0), a1 = softmax_step(s1, m1, l1);
.LBB0_810:
	s_bitcmp1_b32 s8, 0
	s_cselect_b32 s9, 0x9000, 0
	v_or_b32_e32 v120, s9, v199
	v_add_u32_e32 v219, v120, v200
	v_add_u32_e32 v202, v120, v201
	ds_read_b128 v[112:115], v219
	ds_read_b128 v[116:119], v219 offset:2048
	ds_read_b128 v[120:123], v202
	ds_read_b128 v[124:127], v202 offset:2048
	s_waitcnt lgkmcnt(3)
	v_mfma_f32_16x16x32_f16 v[112:115], v[112:115], v[0:3], 0
	s_mov_b32 s9, 0xff800000
	s_waitcnt lgkmcnt(1)
	v_mfma_f32_16x16x32_f16 v[136:139], v[120:123], v[8:11], v[112:115]
	s_nop 4
	ds_read_b128 v[112:115], v219 offset:4096
	ds_read_b128 v[120:123], v202 offset:4096
	v_mfma_f32_16x16x32_f16 v[116:119], v[116:119], v[0:3], 0
	s_waitcnt lgkmcnt(1)
	v_mfma_f32_16x16x32_f16 v[112:115], v[112:115], v[0:3], 0
	v_mfma_f32_16x16x32_f16 v[128:131], v[124:127], v[8:11], v[116:119]
	s_nop 4
	ds_read_b128 v[116:119], v219 offset:6144
	ds_read_b128 v[140:143], v219 offset:9216
	ds_read_b128 v[124:127], v202 offset:6144
	ds_read_b128 v[144:147], v202 offset:9216
	ds_read_b128 v[204:207], v219 offset:11264
	ds_read_b128 v[210:213], v219 offset:13312
	s_waitcnt lgkmcnt(6)
	v_mfma_f32_16x16x32_f16 v[132:135], v[120:123], v[8:11], v[112:115]
	ds_read_b128 v[120:123], v202 offset:11264
	ds_read_b128 v[220:223], v202 offset:13312
	ds_read_b128 v[224:227], v219 offset:15360
	s_waitcnt lgkmcnt(8)
	v_mfma_f32_16x16x32_f16 v[112:115], v[116:119], v[0:3], 0
	v_max_f32_e32 v116, v138, v139
	v_max3_f32 v203, v136, v137, v116
	v_max_f32_e32 v116, v130, v131
	s_waitcnt lgkmcnt(6)
	v_mfma_f32_16x16x32_f16 v[124:127], v[124:127], v[8:11], v[112:115]
	v_mfma_f32_16x16x32_f16 v[112:115], v[140:143], v[4:7], 0
	v_max3_f32 v140, v128, v129, v116
	v_max_f32_e32 v141, v132, v133
	s_waitcnt lgkmcnt(4)
	v_mfma_f32_16x16x32_f16 v[116:119], v[204:207], v[4:7], 0
	v_max_f32_e32 v142, v134, v135
	s_waitcnt lgkmcnt(2)
	v_mfma_f32_16x16x32_f16 v[116:119], v[120:123], v[12:15], v[116:119]
	v_max_f32_e32 v120, v126, v127
	v_max3_f32 v143, v124, v125, v120
	v_max3_f32 v141, v141, v142, v143
	v_mfma_f32_16x16x32_f16 v[112:115], v[144:147], v[12:15], v[112:115]
	v_max3_f32 v144, v203, v140, v141
	ds_bpermute_b32 v145, v189, v144
	ds_read_b128 v[140:143], v202 offset:15360
	v_mfma_f32_16x16x32_f16 v[120:123], v[210:213], v[4:7], 0
	s_waitcnt lgkmcnt(1)
	v_max_f32_e32 v203, v144, v145
	ds_bpermute_b32 v204, v188, v203
	v_mfma_f32_16x16x32_f16 v[144:147], v[224:227], v[4:7], 0
	s_waitcnt lgkmcnt(1)
	v_mfma_f32_16x16x32_f16 v[232:235], v[140:143], v[12:15], v[144:147]
	v_mfma_f32_16x16x32_f16 v[120:123], v[220:223], v[12:15], v[120:123]
	s_waitcnt lgkmcnt(0)
	s_nop 3
	v_max3_f32 v146, v209, v203, v204
	v_cmp_neq_f32_e32 vcc, s9, v146
	ds_read_b128 v[220:223], v219 offset:32768
	ds_read_b128 v[224:227], v219 offset:18432
	ds_read_b128 v[228:231], v202 offset:18432
	v_cndmask_b32_e32 v141, 0, v146, vcc
	v_sub_f32_e32 v136, v136, v141
	v_sub_f32_e32 v128, v128, v141
	v_exp_f32_e32 v203, v136
	v_sub_f32_e32 v136, v137, v141
	v_exp_f32_e32 v207, v128
	v_sub_f32_e32 v128, v129, v141
	v_sub_f32_e32 v129, v131, v141
	v_exp_f32_e32 v204, v136
	v_sub_f32_e32 v136, v138, v141
	v_exp_f32_e32 v208, v128
	v_sub_f32_e32 v128, v130, v141
	v_exp_f32_e32 v130, v129
	v_sub_f32_e32 v129, v132, v141
	v_exp_f32_e32 v205, v136
	v_sub_f32_e32 v136, v139, v141
	v_exp_f32_e32 v132, v129
	v_sub_f32_e32 v129, v133, v141
	v_exp_f32_e32 v206, v136
	v_exp_f32_e32 v136, v129
	v_sub_f32_e32 v129, v134, v141
	v_exp_f32_e32 v134, v129
	v_sub_f32_e32 v129, v135, v141
	v_exp_f32_e32 v138, v129
	v_max_f32_e32 v129, v114, v115
	v_max_f32_e32 v131, v118, v119
	v_max_f32_e32 v133, v120, v121
	v_max_f32_e32 v135, v122, v123
	v_max_f32_e32 v137, v234, v235
	v_max3_f32 v137, v232, v233, v137
	v_max3_f32 v129, v112, v113, v129
	v_max3_f32 v131, v116, v117, v131
	v_max3_f32 v133, v133, v135, v137
	v_max3_f32 v129, v129, v131, v133
	v_mov_b32_e32 v131, v129
	v_sub_f32_e32 v125, v125, v141
	v_exp_f32_e32 v140, v125
	v_sub_f32_e32 v125, v126, v141
	v_exp_f32_e32 v126, v125
	s_waitcnt lgkmcnt(0)
	s_nop 1
	v_permlane16_swap_b32_e32 v129, v131
	v_max_f32_e32 v125, v129, v131
	v_mov_b32_e32 v129, v125
	v_sub_f32_e32 v127, v127, v141
	v_exp_f32_e32 v142, v127
	v_sub_f32_e32 v127, v209, v141
	v_exp_f32_e32 v128, v128
	s_waitcnt lgkmcnt(0)
; #define MFMA16(a, b, c) __builtin_amdgcn_mfma_f32_16x16x32_f16((a), (b), (c), 0, 0, 0)
; DI float softmax_step(f32x4 (&st)[4], float& m, float& lsum) {
;     ...
;   const float alpha = __builtin_amdgcn_exp2f(m - mu);
;   float ps = 0.f;
; #pragma unroll
;   for (int kt = 0; kt < 4; ++kt)
; #pragma unroll
;     for (int j = 0; j < 4; ++j) { const float p = __builtin_amdgcn_exp2f(st[kt][j] - mu); st[kt][j] = p; ps += p; }
;   lsum = lsum * alpha + ps; m = mn;
;   return alpha;
; DI void attn_A(const Params& P, int l, int b, int head, int qt, float lam, char* smem, bf16_t* ybase, size_t ypitch) {
;     ...
;     const float a0 = softmax_step(s0, m0, l0), a1 = softmax_step(s1, m1, l1);
; #pragma unroll
;     for (int i = 0; i < 8; ++i) { o0[i] *= a0; o1[i] *= a1; }
; #pragma unroll
;     for (int kk = 0; kk < 2; ++kk) {
;       const bf16x8 p0 = pack8(s0[2 * kk], s0[2 * kk + 1]), p1 = pack8(s1[2 * kk], s1[2 * kk + 1]);
; #pragma unroll
;       for (int dt = 0; dt < 8; ++dt) {
;         const bf16x8 vf = vfrag(sb + 18432, dt, kk, lr, g);
;         o0[dt] = MFMA16(vf, p0, o0[dt]);
;         o1[dt] = MFMA16(vf, p1, o1[dt]);
;       }
;     }
	s_nop 1
	v_permlane32_swap_b32_e32 v125, v129
	v_max3_f32 v147, v215, v125, v129
	v_cmp_neq_f32_e32 vcc, s9, v147
	v_exp_f32_e32 v144, v127
	ds_read_b128 v[236:239], v219 offset:20480
	v_cndmask_b32_e32 v143, 0, v147, vcc
	v_sub_f32_e32 v112, v112, v143
	v_exp_f32_e32 v209, v112
	v_sub_f32_e32 v112, v113, v143
	v_exp_f32_e32 v210, v112
	v_sub_f32_e32 v112, v114, v143
	v_exp_f32_e32 v211, v112
	v_sub_f32_e32 v112, v115, v143
	v_exp_f32_e32 v212, v112
	v_sub_f32_e32 v112, v116, v143
	v_exp_f32_e32 v213, v112
	v_sub_f32_e32 v112, v117, v143
	v_exp_f32_e32 v214, v112
	v_sub_f32_e32 v112, v118, v143
	v_exp_f32_e32 v129, v112
	v_sub_f32_e32 v112, v119, v143
	v_exp_f32_e32 v131, v112
	v_sub_f32_e32 v112, v120, v143
	v_exp_f32_e32 v133, v112
	v_sub_f32_e32 v112, v121, v143
	v_exp_f32_e32 v137, v112
	v_sub_f32_e32 v112, v122, v143
	v_exp_f32_e32 v135, v112
	v_sub_f32_e32 v112, v215, v143
	v_exp_f32_e32 v120, v112
	v_sub_f32_e32 v121, v123, v143
	v_cvt_pk_f16_f32 v112, v203, v204
	v_cvt_pk_f16_f32 v113, v205, v206
	v_cvt_pk_f16_f32 v114, v207, v208
	v_cvt_pk_f16_f32 v116, v209, v210
	v_cvt_pk_f16_f32 v117, v211, v212
	v_cvt_pk_f16_f32 v118, v213, v214
	v_pk_mul_f32 v[94:95], v[94:95], v[144:145] op_sel_hi:[1,0]
	v_pk_mul_f32 v[92:93], v[92:93], v[144:145] op_sel_hi:[1,0]
	v_cvt_pk_f16_f32 v115, v128, v130
	v_pk_mul_f32 v[102:103], v[102:103], v[120:121] op_sel_hi:[1,0]
	v_pk_mul_f32 v[100:101], v[100:101], v[120:121] op_sel_hi:[1,0]
	v_cvt_pk_f16_f32 v119, v129, v131
	v_mfma_f32_16x16x32_f16 v[92:95], v[224:227], v[112:115], v[92:95]
	v_exp_f32_e32 v139, v121
	v_pk_mul_f32 v[98:99], v[98:99], v[120:121] op_sel_hi:[1,0]
	v_pk_mul_f32 v[96:97], v[96:97], v[120:121] op_sel_hi:[1,0]
	v_mfma_f32_16x16x32_f16 v[100:103], v[224:227], v[116:119], v[100:103]
	ds_read_b128 v[224:227], v219 offset:22528
	v_sub_f32_e32 v121, v232, v143
	v_pk_mul_f32 v[90:91], v[90:91], v[120:121] op_sel_hi:[1,0]
	v_pk_mul_f32 v[88:89], v[88:89], v[120:121] op_sel_hi:[1,0]
	v_exp_f32_e32 v125, v121
	v_pk_mul_f32 v[82:83], v[82:83], v[120:121] op_sel_hi:[1,0]
	v_pk_mul_f32 v[80:81], v[80:81], v[120:121] op_sel_hi:[1,0]
	v_sub_f32_e32 v121, v233, v143
	v_sub_f32_e32 v124, v124, v141
	v_pk_mul_f32 v[74:75], v[74:75], v[120:121] op_sel_hi:[1,0]
	v_pk_mul_f32 v[72:73], v[72:73], v[120:121] op_sel_hi:[1,0]
	v_exp_f32_e32 v141, v121
	v_pk_mul_f32 v[62:63], v[62:63], v[120:121] op_sel_hi:[1,0]
	v_pk_mul_f32 v[60:61], v[60:61], v[120:121] op_sel_hi:[1,0]
	v_sub_f32_e32 v121, v234, v143
	v_exp_f32_e32 v127, v121
	v_pk_mul_f32 v[50:51], v[50:51], v[120:121] op_sel_hi:[1,0]
	v_pk_mul_f32 v[48:49], v[48:49], v[120:121] op_sel_hi:[1,0]
	v_sub_f32_e32 v121, v235, v143
	v_pk_mul_f32 v[86:87], v[86:87], v[144:145] op_sel_hi:[1,0]
	v_pk_mul_f32 v[84:85], v[84:85], v[144:145] op_sel_hi:[1,0]
	v_pk_mul_f32 v[78:79], v[78:79], v[144:145] op_sel_hi:[1,0]
	v_pk_mul_f32 v[76:77], v[76:77], v[144:145] op_sel_hi:[1,0]
	v_pk_mul_f32 v[106:107], v[106:107], v[144:145] op_sel_hi:[1,0]
	v_pk_mul_f32 v[104:105], v[104:105], v[144:145] op_sel_hi:[1,0]
	v_pk_mul_f32 v[110:111], v[110:111], v[120:121] op_sel_hi:[1,0]
	v_pk_mul_f32 v[108:109], v[108:109], v[120:121] op_sel_hi:[1,0]
	v_mfma_f32_16x16x32_f16 v[104:107], v[220:223], v[112:115], v[104:107]
	v_mul_f32_e64 v70, v70, v144
	v_mul_f32_e64 v71, v71, v144
	v_pk_mul_f32 v[68:69], v[68:69], v[144:145] op_sel_hi:[1,0]
	v_pk_mul_f32 v[58:59], v[58:59], v[144:145] op_sel_hi:[1,0]
	v_mfma_f32_16x16x32_f16 v[108:111], v[220:223], v[116:119], v[108:111]
	ds_read_b128 v[220:223], v202 offset:20480
	v_pk_mul_f32 v[56:57], v[56:57], v[144:145] op_sel_hi:[1,0]
	v_exp_f32_e32 v124, v124
	s_waitcnt lgkmcnt(2)
	v_mfma_f32_16x16x32_f16 v[84:87], v[236:239], v[112:115], v[84:87]
	v_exp_f32_e32 v143, v121
	v_pk_mul_f32 v[46:47], v[46:47], v[144:145] op_sel_hi:[1,0]
	v_pk_mul_f32 v[44:45], v[44:45], v[144:145] op_sel_hi:[1,0]
	v_mfma_f32_16x16x32_f16 v[96:99], v[236:239], v[116:119], v[96:99]
	ds_read_b128 v[236:239], v219 offset:24576
	v_pk_mul_f32 v[42:43], v[42:43], v[144:145] op_sel_hi:[1,0]
	v_pk_mul_f32 v[40:41], v[40:41], v[144:145] op_sel_hi:[1,0]
	s_waitcnt lgkmcnt(2)
	v_mfma_f32_16x16x32_f16 v[76:79], v[224:227], v[112:115], v[76:79]
	s_andn2_b64 vcc, exec, s[6:7]
	v_mfma_f32_16x16x32_f16 v[88:91], v[224:227], v[116:119], v[88:91]
	ds_read_b128 v[224:227], v219 offset:26624
	s_waitcnt lgkmcnt(1)
	v_mfma_f32_16x16x32_f16 v[68:71], v[236:239], v[112:115], v[68:71]
	v_mfma_f32_16x16x32_f16 v[80:83], v[236:239], v[116:119], v[80:83]
	ds_read_b128 v[236:239], v219 offset:28672
	s_waitcnt lgkmcnt(1)
	v_mfma_f32_16x16x32_f16 v[56:59], v[224:227], v[112:115], v[56:59]
	v_mfma_f32_16x16x32_f16 v[72:75], v[224:227], v[116:119], v[72:75]
	ds_read_b128 v[224:227], v219 offset:30720
	s_waitcnt lgkmcnt(1)
	v_mfma_f32_16x16x32_f16 v[44:47], v[236:239], v[112:115], v[44:47]
	v_mfma_f32_16x16x32_f16 v[60:63], v[236:239], v[116:119], v[60:63]
	s_waitcnt lgkmcnt(0)
	v_mfma_f32_16x16x32_f16 v[40:43], v[224:227], v[112:115], v[40:43]
	v_cvt_pk_f16_f32 v112, v133, v137
	v_cvt_pk_f16_f32 v113, v135, v139
	v_cvt_pk_f16_f32 v114, v125, v141
	v_mfma_f32_16x16x32_f16 v[48:51], v[224:227], v[116:119], v[48:51]
	v_cvt_pk_f16_f32 v116, v132, v136
	v_cvt_pk_f16_f32 v117, v134, v138
	v_cvt_pk_f16_f32 v118, v124, v140
	v_cvt_pk_f16_f32 v119, v126, v142
	v_cvt_pk_f16_f32 v115, v127, v143
	s_nop 0
	v_mfma_f32_16x16x32_f16 v[84:87], v[220:223], v[116:119], v[84:87]
	v_mfma_f32_16x16x32_f16 v[96:99], v[220:223], v[112:115], v[96:99]
	ds_read_b128 v[220:223], v202 offset:22528
	s_waitcnt lgkmcnt(0)
	v_mfma_f32_16x16x32_f16 v[76:79], v[220:223], v[116:119], v[76:79]
	v_mfma_f32_16x16x32_f16 v[88:91], v[220:223], v[112:115], v[88:91]
	ds_read_b128 v[220:223], v202 offset:24576
	s_waitcnt lgkmcnt(0)
	v_mfma_f32_16x16x32_f16 v[68:71], v[220:223], v[116:119], v[68:71]
	v_mfma_f32_16x16x32_f16 v[80:83], v[220:223], v[112:115], v[80:83]
	ds_read_b128 v[220:223], v202 offset:26624
	s_waitcnt lgkmcnt(0)
	v_mfma_f32_16x16x32_f16 v[56:59], v[220:223], v[116:119], v[56:59]
	v_mfma_f32_16x16x32_f16 v[72:75], v[220:223], v[112:115], v[72:75]
	ds_read_b128 v[220:223], v202 offset:28672
	s_waitcnt lgkmcnt(0)
	v_mfma_f32_16x16x32_f16 v[44:47], v[220:223], v[116:119], v[44:47]
	v_mfma_f32_16x16x32_f16 v[60:63], v[220:223], v[112:115], v[60:63]
	ds_read_b128 v[220:223], v202 offset:30720
	s_waitcnt lgkmcnt(0)
	v_mfma_f32_16x16x32_f16 v[40:43], v[220:223], v[116:119], v[40:43]
	v_mfma_f32_16x16x32_f16 v[48:51], v[220:223], v[112:115], v[48:51]
	ds_read_b128 v[220:223], v202 offset:32768
	v_mfma_f32_16x16x32_f16 v[92:95], v[228:231], v[116:119], v[92:95]
	v_mfma_f32_16x16x32_f16 v[100:103], v[228:231], v[112:115], v[100:103]
	s_waitcnt lgkmcnt(0)
	v_mfma_f32_16x16x32_f16 v[104:107], v[220:223], v[116:119], v[104:107]
	v_mfma_f32_16x16x32_f16 v[108:111], v[220:223], v[112:115], v[108:111]
	s_cbranch_vccnz .LBB0_807
; DI void st_chunk_v(char* sdst, int c, const uint4& v) {
;   const int row = c >> 3, c8 = c & 7, kk = c8 >> 2, cc = c8 & 3, sw = (row >> 1) & 7;
;   const int gq = (cc & 1) * 2, part = cc >> 1;
;   char* base = sdst + row * 128 + part * 8;
;   *(uint2*)(base + (((kk * 4 + gq) ^ sw) << 4)) = make_uint2(v.x, v.y);
;   *(uint2*)(base + (((kk * 4 + gq + 1) ^ sw) << 4)) = make_uint2(v.z, v.w);
; }
; DI void gload2(R2& r, const bf16_t* gsrc, size_t gp, int tid) { r.a = ld_chunk(gsrc, gp, tid); r.b = ld_chunk(gsrc, gp, tid + 256); }
; DI void gload4(R4& r, const bf16_t* gsrc, size_t gp, int tid) { r.a = ld_chunk(gsrc, gp, tid); r.b = ld_chunk(gsrc, gp, tid + 256); r.c = ld_chunk(gsrc, gp, tid + 512); r.d = ld_chunk(gsrc, gp, tid + 768); }
; DI void sstoreK2(const R2& r, char* sdst, int tid) { st_chunk_k(sdst, tid, r.a); st_chunk_k(sdst, tid + 256, r.b); }
; DI void sstoreV2(const R2& r, char* sdst, int tid) { st_chunk_v(sdst, tid, r.a); st_chunk_v(sdst, tid + 256, r.b); }
; DI void sstoreV4(const R4& r, char* sdst, int tid) { st_chunk_v(sdst, tid, r.a); st_chunk_v(sdst, tid + 256, r.b); st_chunk_v(sdst, tid + 512, r.c); st_chunk_v(sdst, tid + 768, r.d); }
; DI void attn_A(const Params& P, int l, int b, int head, int qt, float lam, char* smem, bf16_t* ybase, size_t ypitch) {
;     ...
;     if (n < qt) {
;       char* sn = smem + ((n + 1) & 1) * STAGE;
;       sstoreK2(rk0, sn, tid); sstoreK2(rk1, sn + 9216, tid); sstoreV4(rv, sn + 18432, tid);
;     }
;     __syncthreads();
	s_andn2_b32 s6, 1, s8
	s_mul_i32 s6, s6, 0x9000
	v_add_u32_e32 v112, s6, v155
	v_add_u32_e32 v113, v112, v195
	v_add_u32_e32 v112, v112, v196
	s_waitcnt vmcnt(7)
	ds_write_b128 v113, v[16:19]
	s_waitcnt vmcnt(5)
	ds_write_b128 v113, v[20:23] offset:4096
	ds_write_b128 v113, v[24:27] offset:9216
	s_waitcnt vmcnt(4)
	ds_write_b128 v113, v[28:31] offset:13312
	v_add_u32_e32 v113, v112, v197
	v_add_u32_e32 v112, v112, v198
	s_waitcnt vmcnt(2)
	ds_write2st64_b64 v113, v[32:33], v[36:37] offset0:36 offset1:44
	ds_write2st64_b64 v112, v[34:35], v[38:39] offset0:36 offset1:44
	s_waitcnt vmcnt(0)
	ds_write2st64_b64 v113, v[52:53], v[64:65] offset0:52 offset1:60
	ds_write2st64_b64 v112, v[54:55], v[66:67] offset0:52 offset1:60
	s_branch .LBB0_807

; #define MFMA16(a, b, c) __builtin_amdgcn_mfma_f32_16x16x32_f16((a), (b), (c), 0, 0, 0)
; DI void qk_tile2(f32x4 (&sa)[4], f32x4 (&sb)[4], const char* sK, const bf16x8 (&qa)[2], const bf16x8 (&qb)[2], int lr, int g) {
; #pragma unroll
;   for (int kt = 0; kt < 4; ++kt) {
;     const bf16x8 k0 = *(const bf16x8*)(sK + (kt * 16 + lr) * 128 + ((g ^ ((lr >> 1) & 7)) << 4)), k1 = *(const bf16x8*)(sK + (kt * 16 + lr) * 128 + (((4 + g) ^ ((lr >> 1) & 7)) << 4));
;     sa[kt] = MFMA16(k0, qa[0], ((f32x4){0.f, 0.f, 0.f, 0.f})); sb[kt] = MFMA16(k0, qb[0], ((f32x4){0.f, 0.f, 0.f, 0.f}));
;     sa[kt] = MFMA16(k1, qa[1], sa[kt]); sb[kt] = MFMA16(k1, qb[1], sb[kt]);
;   }
; }
.LBB0_1079:
	v_readlane_b32 s16, v254, 55
	s_add_i32 s1, s15, -2
	v_readlane_b32 s18, v254, 57
	v_readlane_b32 s19, v254, 58
	v_cmp_le_i32_e32 vcc, s1, v107
	v_readlane_b32 s17, v254, 56
	v_lshl_add_u64 v[122:123], s[18:19], 0, v[112:113]
	s_and_saveexec_b64 s[12:13], vcc
	s_cbranch_execz .LBB0_1081
	v_add_co_u32_e32 v80, vcc, 0x1b900000, v122
	s_mov_b32 s16, 0xff800000
	s_nop 0
	v_addc_co_u32_e32 v81, vcc, 0, v123, vcc
	global_load_dwordx2 v[126:127], v[80:81], off
	v_add_co_u32_e32 v80, vcc, 0x1b902000, v122
	s_waitcnt vmcnt(0)
	v_lshrrev_b32_e32 v147, v132, v126
	v_addc_co_u32_e32 v81, vcc, 0, v123, vcc
	global_load_dwordx2 v[128:129], v[80:81], off
	ds_read_b128 v[80:83], v139
	ds_read_b128 v[84:87], v140
	s_waitcnt lgkmcnt(1)
	v_mfma_f32_16x16x32_f16 v[88:91], v[80:83], v[0:3], 0
	v_and_b32_e32 v130, 1, v147
	v_cmp_eq_u32_e32 vcc, 1, v130
	v_bfe_i32 v141, v147, 1, 1
	v_mfma_f32_16x16x32_f16 v[80:83], v[80:83], v[4:7], 0
	v_lshrrev_b32_e32 v126, v138, v126
	s_waitcnt lgkmcnt(0)
	v_mfma_f32_16x16x32_f16 v[142:145], v[84:87], v[8:11], v[88:91]
	v_mfma_f32_16x16x32_f16 v[154:157], v[84:87], v[12:15], v[80:83]
	s_nop 3
	ds_read_b128 v[80:83], v139 offset:2048
	ds_read_b128 v[84:87], v140 offset:2048
	s_waitcnt lgkmcnt(1)
	v_mfma_f32_16x16x32_f16 v[88:91], v[80:83], v[0:3], 0
	v_mfma_f32_16x16x32_f16 v[80:83], v[80:83], v[4:7], 0
	s_waitcnt lgkmcnt(0)
	v_mfma_f32_16x16x32_f16 v[100:103], v[84:87], v[8:11], v[88:91]
	v_mfma_f32_16x16x32_f16 v[96:99], v[84:87], v[12:15], v[80:83]
	s_nop 4
	ds_read_b128 v[80:83], v139 offset:4096
	ds_read_b128 v[88:91], v140 offset:4096
	s_waitcnt lgkmcnt(1)
	v_mfma_f32_16x16x32_f16 v[84:87], v[80:83], v[0:3], 0
	v_mfma_f32_16x16x32_f16 v[80:83], v[80:83], v[4:7], 0
	s_waitcnt lgkmcnt(0)
	v_mfma_f32_16x16x32_f16 v[84:87], v[88:91], v[8:11], v[84:87]
	v_mfma_f32_16x16x32_f16 v[80:83], v[88:91], v[12:15], v[80:83]
	ds_read_b128 v[88:91], v139 offset:6144
	ds_read_b128 v[92:95], v140 offset:6144
	s_waitcnt lgkmcnt(1)
	v_mfma_f32_16x16x32_f16 v[158:161], v[88:91], v[0:3], 0
	v_mfma_f32_16x16x32_f16 v[162:165], v[88:91], v[4:7], 0
	s_waitcnt lgkmcnt(0)
	v_mfma_f32_16x16x32_f16 v[88:91], v[92:95], v[8:11], v[158:161]
	s_nop 4
	v_cndmask_b32_e32 v159, v187, v142, vcc
	v_bfe_i32 v142, v147, 2, 1
	v_mfma_f32_16x16x32_f16 v[92:95], v[92:95], v[12:15], v[162:165]
	s_waitcnt vmcnt(0)
	v_lshrrev_b32_e32 v158, v132, v128
	v_and_b32_e32 v130, 1, v158
	v_cmp_eq_u32_e32 vcc, 1, v130
	v_lshrrev_b32_e32 v128, v138, v128
	s_nop 0
	v_cndmask_b32_e32 v130, v187, v154, vcc
	v_bfi_b32 v154, v141, v143, v187
	v_and_b32_e32 v141, 2, v158
	v_cmp_ne_u32_e32 vcc, 0, v141
	v_bfe_i32 v143, v147, 3, 1
	v_bfe_i32 v147, v126, 0, 1
	v_cndmask_b32_e32 v141, v187, v155, vcc
	v_bfi_b32 v144, v142, v144, v187
	v_and_b32_e32 v142, 4, v158
	v_cmp_ne_u32_e32 vcc, 0, v142
	s_nop 1
	v_cndmask_b32_e32 v142, v187, v156, vcc
	v_bfi_b32 v145, v143, v145, v187
	v_and_b32_e32 v143, 8, v158
	v_cmp_ne_u32_e32 vcc, 0, v143
	s_nop 1
	v_cndmask_b32_e32 v143, v187, v157, vcc
	v_bfi_b32 v100, v147, v100, v187
	v_and_b32_e32 v147, 1, v128
	v_cmp_eq_u32_e32 vcc, 1, v147
	s_nop 1
	v_cndmask_b32_e32 v147, v187, v96, vcc
	v_and_b32_e32 v96, 2, v126
	v_cmp_ne_u32_e32 vcc, 0, v96
	s_nop 1
	v_cndmask_b32_e32 v96, v187, v101, vcc
	v_bfe_i32 v101, v128, 1, 1
	v_bfi_b32 v97, v101, v97, v187
	v_and_b32_e32 v101, 4, v126
	v_cmp_ne_u32_e32 vcc, 0, v101
	s_nop 1
	v_cndmask_b32_e32 v101, v187, v102, vcc
	v_bfe_i32 v102, v128, 2, 1
	v_bfi_b32 v98, v102, v98, v187
	v_and_b32_e32 v102, 8, v126
	v_lshrrev_b32_e32 v126, v132, v129
	v_cmp_ne_u32_e32 vcc, 0, v102
	s_nop 1
	v_cndmask_b32_e32 v102, v187, v103, vcc
	v_and_b32_e32 v103, 8, v128
	v_cmp_ne_u32_e32 vcc, 0, v103
	s_nop 1
	v_cndmask_b32_e32 v103, v187, v99, vcc
	v_lshrrev_b32_e32 v99, v132, v127
	v_bfe_i32 v128, v99, 0, 1
	v_bfi_b32 v84, v128, v84, v187
	v_and_b32_e32 v128, 1, v126
	v_cmp_eq_u32_e32 vcc, 1, v128
	s_nop 1
	v_cndmask_b32_e32 v128, v187, v80, vcc
	v_and_b32_e32 v80, 2, v99
	v_cmp_ne_u32_e32 vcc, 0, v80
	s_nop 1
	v_cndmask_b32_e32 v80, v187, v85, vcc
	v_bfe_i32 v85, v126, 1, 1
	v_bfi_b32 v81, v85, v81, v187
	v_and_b32_e32 v85, 4, v99
	v_cmp_ne_u32_e32 vcc, 0, v85
	s_nop 1
	v_cndmask_b32_e32 v85, v187, v86, vcc
	v_bfe_i32 v86, v126, 2, 1
	v_bfi_b32 v155, v86, v82, v187
	v_bfe_i32 v86, v126, 3, 1
	v_and_b32_e32 v82, 8, v99
	v_cmp_ne_u32_e32 vcc, 0, v82
	s_nop 1
	v_cndmask_b32_e32 v82, v187, v87, vcc
	v_bfi_b32 v83, v86, v83, v187
	v_lshrrev_b32_e32 v86, v138, v127
	v_lshrrev_b32_e32 v87, v138, v129
	v_bfe_i32 v99, v86, 0, 1
	v_bfi_b32 v88, v99, v88, v187
	v_bfe_i32 v99, v87, 0, 1
	v_bfi_b32 v126, v99, v92, v187
	v_bfe_i32 v92, v86, 1, 1
	v_bfi_b32 v89, v92, v89, v187
	v_bfe_i32 v92, v87, 1, 1
	v_bfi_b32 v127, v92, v93, v187
	v_bfe_i32 v92, v86, 2, 1
	v_bfe_i32 v86, v86, 3, 1
	v_bfi_b32 v93, v92, v90, v187
	v_bfe_i32 v90, v87, 2, 1
	v_bfi_b32 v129, v90, v94, v187
	v_bfi_b32 v91, v86, v91, v187
	v_bfe_i32 v86, v87, 3, 1
	v_bfi_b32 v156, v86, v95, v187
	v_max_f32_e32 v86, v144, v145
	v_max_f32_e32 v87, v101, v102
	v_max_f32_e32 v90, v84, v80
	v_max_f32_e32 v92, v85, v82
	v_max_f32_e32 v94, v93, v91
	v_max3_f32 v94, v88, v89, v94
	v_max3_f32 v86, v159, v154, v86
	v_max3_f32 v87, v100, v96, v87
	v_max3_f32 v90, v90, v92, v94
	v_max3_f32 v86, v86, v87, v90
	v_mov_b32_e32 v87, v86
	s_waitcnt lgkmcnt(0)
	s_nop 1
	v_permlane16_swap_b32_e32 v86, v87
	v_max_f32_e32 v86, v86, v87
	v_mov_b32_e32 v87, v86
	s_waitcnt lgkmcnt(0)
; DI float softmax_step(f32x4 (&st)[4], float& m, float& lsum) {
;   float mx = fmaxf(fmaxf(fmaxf(st[0][0], st[0][1]), fmaxf(st[0][2], st[0][3])), fmaxf(fmaxf(st[1][0], st[1][1]), fmaxf(st[1][2], st[1][3])));
;   mx = fmaxf(mx, fmaxf(fmaxf(fmaxf(st[2][0], st[2][1]), fmaxf(st[2][2], st[2][3])), fmaxf(fmaxf(st[3][0], st[3][1]), fmaxf(st[3][2], st[3][3]))));
;   mx = fmaxf(mx, __shfl_xor(mx, 16)); mx = fmaxf(mx, __shfl_xor(mx, 32));
;   const float mn = fmaxf(m, mx);
;   const float mu = mn == -INFINITY ? 0.f : mn;
;   const float alpha = __builtin_amdgcn_exp2f(m - mu);
;   float ps = 0.f;
; #pragma unroll
;   for (int kt = 0; kt < 4; ++kt)
; #pragma unroll
;     for (int j = 0; j < 4; ++j) { const float p = __builtin_amdgcn_exp2f(st[kt][j] - mu); st[kt][j] = p; ps += p; }
;   lsum = lsum * alpha + ps; m = mn;
;   return alpha;
	s_nop 1
	v_permlane32_swap_b32_e32 v86, v87
	v_max3_f32 v99, v131, v86, v87
	v_cmp_neq_f32_e32 vcc, s16, v99
	s_nop 1
	v_cndmask_b32_e32 v87, 0, v99, vcc
	v_sub_f32_e32 v86, v159, v87
	v_exp_f32_e32 v162, v86
	v_sub_f32_e32 v86, v154, v87
	v_exp_f32_e32 v164, v86
	v_sub_f32_e32 v86, v144, v87
	v_exp_f32_e32 v166, v86
	v_sub_f32_e32 v86, v145, v87
	v_sub_f32_e32 v80, v80, v87
	v_exp_f32_e32 v168, v86
	v_sub_f32_e32 v86, v100, v87
	v_exp_f32_e32 v94, v80
	v_sub_f32_e32 v80, v85, v87
	v_exp_f32_e32 v170, v86
	v_sub_f32_e32 v86, v96, v87
	v_exp_f32_e32 v92, v80
	v_sub_f32_e32 v80, v82, v87
	v_exp_f32_e32 v190, v86
	v_sub_f32_e32 v86, v101, v87
	v_exp_f32_e32 v90, v80
	v_sub_f32_e32 v80, v88, v87
	v_exp_f32_e32 v192, v86
	v_sub_f32_e32 v86, v102, v87
	v_exp_f32_e32 v88, v80
	v_sub_f32_e32 v80, v89, v87
	v_exp_f32_e32 v194, v86
	v_sub_f32_e32 v84, v84, v87
	v_exp_f32_e32 v86, v80
	v_sub_f32_e32 v80, v93, v87
	v_exp_f32_e32 v96, v84
	v_exp_f32_e32 v82, v80
	v_sub_f32_e32 v80, v91, v87
	v_sub_f32_e32 v84, v131, v87
	v_max_f32_e32 v85, v142, v143
	v_max_f32_e32 v87, v98, v103
	v_max_f32_e32 v89, v128, v81
	v_max_f32_e32 v91, v155, v83
	v_max_f32_e32 v93, v129, v156
	v_max3_f32 v93, v126, v127, v93
	v_max3_f32 v85, v130, v141, v85
	v_max3_f32 v87, v147, v97, v87
	v_max3_f32 v89, v89, v91, v93
	v_max3_f32 v85, v85, v87, v89
	v_mov_b32_e32 v87, v85
	v_exp_f32_e32 v84, v84
	v_exp_f32_e32 v80, v80
	v_mov_b32_e32 v131, v99
	s_waitcnt lgkmcnt(0)
	s_nop 1
	v_permlane16_swap_b32_e32 v85, v87
	v_max_f32_e32 v85, v85, v87
	v_mov_b32_e32 v87, v85
	s_waitcnt lgkmcnt(0)
	s_nop 1
	v_permlane32_swap_b32_e32 v85, v87
	v_max3_f32 v102, v146, v85, v87
	v_cmp_neq_f32_e32 vcc, s16, v102
	s_nop 1
	v_cndmask_b32_e32 v85, 0, v102, vcc
	v_sub_f32_e32 v87, v130, v85
	v_exp_f32_e32 v163, v87
	v_sub_f32_e32 v87, v141, v85
	v_exp_f32_e32 v165, v87
	v_sub_f32_e32 v87, v142, v85
	v_exp_f32_e32 v167, v87
	v_sub_f32_e32 v87, v143, v85
	v_exp_f32_e32 v169, v87
	v_sub_f32_e32 v87, v147, v85
	v_sub_f32_e32 v81, v81, v85
	v_exp_f32_e32 v171, v87
	v_sub_f32_e32 v87, v97, v85
	v_exp_f32_e32 v95, v81
	v_sub_f32_e32 v81, v155, v85
	v_exp_f32_e32 v191, v87
	v_sub_f32_e32 v87, v98, v85
	v_exp_f32_e32 v93, v81
	v_sub_f32_e32 v81, v83, v85
	v_exp_f32_e32 v193, v87
	v_sub_f32_e32 v87, v103, v85
	v_exp_f32_e32 v91, v81
	v_sub_f32_e32 v81, v126, v85
	v_exp_f32_e32 v195, v87
	v_sub_f32_e32 v87, v128, v85
	v_exp_f32_e32 v89, v81
	v_sub_f32_e32 v81, v127, v85
	v_exp_f32_e32 v97, v87
	v_exp_f32_e32 v87, v81
	v_sub_f32_e32 v81, v129, v85
	v_exp_f32_e32 v83, v81
	v_sub_f32_e32 v81, v156, v85
	v_sub_f32_e32 v85, v146, v85
	v_exp_f32_e32 v98, v85
	v_pk_mul_f32 v[156:157], v[70:71], v[84:85] op_sel_hi:[1,0]
	v_pk_mul_f32 v[154:155], v[68:69], v[84:85] op_sel_hi:[1,0]
	v_pk_mul_f32 v[128:129], v[62:63], v[84:85] op_sel_hi:[1,0]
	v_pk_mul_f32 v[142:143], v[56:57], v[98:99] op_sel_hi:[1,0]
	v_pk_mul_f32 v[70:71], v[50:51], v[98:99] op_sel_hi:[1,0]
	v_pk_mul_f32 v[68:69], v[48:49], v[98:99] op_sel_hi:[1,0]
	v_pk_mul_f32 v[50:51], v[74:75], v[84:85] op_sel_hi:[1,0]
	v_pk_mul_f32 v[48:49], v[72:73], v[84:85] op_sel_hi:[1,0]
	v_pk_add_f32 v[56:57], v[162:163], 0 op_sel_hi:[1,0]
	ds_read_b128 v[72:75], v139 offset:9216
	v_pk_add_f32 v[56:57], v[164:165], v[56:57]
	v_pk_mul_f32 v[126:127], v[60:61], v[84:85] op_sel_hi:[1,0]
	v_pk_add_f32 v[56:57], v[166:167], v[56:57]
	v_pk_mul_f32 v[144:145], v[58:59], v[98:99] op_sel_hi:[1,0]
	v_pk_add_f32 v[56:57], v[168:169], v[56:57]
	v_cvt_pk_f16_f32 v58, v170, v190
	v_pk_add_f32 v[56:57], v[170:171], v[56:57]
	v_cvt_pk_f16_f32 v59, v192, v194
	v_pk_add_f32 v[56:57], v[190:191], v[56:57]
	v_pk_mul_f32 v[160:161], v[66:67], v[98:99] op_sel_hi:[1,0]
	v_pk_add_f32 v[56:57], v[192:193], v[56:57]
	v_pk_mul_f32 v[158:159], v[64:65], v[98:99] op_sel_hi:[1,0]
	v_pk_add_f32 v[56:57], v[194:195], v[56:57]
	v_pk_mul_f32 v[66:67], v[54:55], v[84:85] op_sel_hi:[1,0]
	v_pk_add_f32 v[100:101], v[96:97], v[56:57]
	v_cvt_pk_f16_f32 v56, v162, v164
	v_cvt_pk_f16_f32 v57, v166, v168
	v_pk_mul_f32 v[64:65], v[52:53], v[84:85] op_sel_hi:[1,0]
	v_pk_mul_f32 v[54:55], v[78:79], v[98:99] op_sel_hi:[1,0]
	v_pk_mul_f32 v[52:53], v[76:77], v[98:99] op_sel_hi:[1,0]
	s_waitcnt lgkmcnt(0)
	v_mfma_f32_16x16x32_f16 v[76:79], v[72:75], v[56:59], v[126:129]
	v_cvt_pk_f16_f32 v60, v163, v165
	v_cvt_pk_f16_f32 v61, v167, v169
	v_cvt_pk_f16_f32 v62, v171, v191
	ds_read_b128 v[126:129], v139 offset:11264
	v_cvt_pk_f16_f32 v63, v193, v195
	v_exp_f32_e32 v81, v81
	v_cvt_pk_f16_f32 v190, v96, v94
	v_mfma_f32_16x16x32_f16 v[72:75], v[72:75], v[60:63], v[142:145]
	v_cvt_pk_f16_f32 v191, v92, v90
	v_cvt_pk_f16_f32 v192, v88, v86
	v_cvt_pk_f16_f32 v193, v82, v80
	s_waitcnt lgkmcnt(0)
	v_mfma_f32_16x16x32_f16 v[142:145], v[126:129], v[56:59], v[154:157]
	v_cvt_pk_f16_f32 v194, v97, v95
	v_cvt_pk_f16_f32 v195, v93, v91
	s_nop 0
	ds_read_b128 v[154:157], v139 offset:13312
	v_mfma_f32_16x16x32_f16 v[126:129], v[126:129], v[60:63], v[158:161]
	v_cvt_pk_f16_f32 v196, v89, v87
	v_cvt_pk_f16_f32 v197, v83, v81
	v_pk_add_f32 v[94:95], v[94:95], v[100:101]
	s_waitcnt lgkmcnt(0)
	v_mfma_f32_16x16x32_f16 v[158:161], v[154:157], v[56:59], v[64:67]
	s_nop 2
	ds_read_b128 v[64:67], v139 offset:15360
	v_pk_add_f32 v[92:93], v[92:93], v[94:95]
	v_mov_b32_e32 v85, v98
	s_waitcnt lgkmcnt(0)
	v_mfma_f32_16x16x32_f16 v[162:165], v[64:67], v[56:59], v[48:51]
	s_nop 2
	ds_read_b128 v[48:51], v140 offset:9216
	v_pk_add_f32 v[90:91], v[90:91], v[92:93]
	v_mov_b32_e32 v146, v102
	v_mfma_f32_16x16x32_f16 v[154:157], v[154:157], v[60:63], v[68:71]
	v_add_f32_e64 v88, v88, v90
	v_add_f32_e64 v89, v89, v91
	v_pk_add_f32 v[86:87], v[86:87], v[88:89]
	v_mfma_f32_16x16x32_f16 v[166:169], v[64:67], v[60:63], v[52:55]
	v_add_f32_e64 v82, v82, v86
	v_add_f32_e64 v83, v83, v87
	v_pk_add_f32 v[80:81], v[80:81], v[82:83]
	s_waitcnt lgkmcnt(0)
	v_mfma_f32_16x16x32_f16 v[60:63], v[48:51], v[190:193], v[76:79]
	v_fma_f32 v118, v118, v84, v80
	v_fma_f32 v119, v119, v85, v81
	v_mfma_f32_16x16x32_f16 v[56:59], v[48:51], v[194:197], v[72:75]
	ds_read_b128 v[48:51], v140 offset:11264
	ds_read_b128 v[76:79], v140 offset:15360
	s_waitcnt lgkmcnt(1)
	v_mfma_f32_16x16x32_f16 v[68:71], v[48:51], v[190:193], v[142:145]
	v_mfma_f32_16x16x32_f16 v[64:67], v[48:51], v[194:197], v[126:129]
	ds_read_b128 v[48:51], v140 offset:13312
	s_waitcnt lgkmcnt(0)
	v_mfma_f32_16x16x32_f16 v[52:55], v[48:51], v[190:193], v[158:161]
	v_mfma_f32_16x16x32_f16 v[48:51], v[48:51], v[194:197], v[154:157]
	v_mfma_f32_16x16x32_f16 v[72:75], v[76:79], v[190:193], v[162:165]
	v_mfma_f32_16x16x32_f16 v[76:79], v[76:79], v[194:197], v[166:169]

; #define MFMA16(a, b, c) __builtin_amdgcn_mfma_f32_16x16x32_f16((a), (b), (c), 0, 0, 0)
; DI void qk_tile2(f32x4 (&sa)[4], f32x4 (&sb)[4], const char* sK, const bf16x8 (&qa)[2], const bf16x8 (&qb)[2], int lr, int g) {
; #pragma unroll
;   for (int kt = 0; kt < 4; ++kt) {
;     const bf16x8 k0 = *(const bf16x8*)(sK + (kt * 16 + lr) * 128 + ((g ^ ((lr >> 1) & 7)) << 4)), k1 = *(const bf16x8*)(sK + (kt * 16 + lr) * 128 + (((4 + g) ^ ((lr >> 1) & 7)) << 4));
;     sa[kt] = MFMA16(k0, qa[0], ((f32x4){0.f, 0.f, 0.f, 0.f})); sb[kt] = MFMA16(k0, qb[0], ((f32x4){0.f, 0.f, 0.f, 0.f}));
;     sa[kt] = MFMA16(k1, qa[1], sa[kt]); sb[kt] = MFMA16(k1, qb[1], sb[kt]);
;   }
; }
.LBB0_1085:
	v_add_co_u32_e32 v80, vcc, 0x1b900000, v122
	s_mov_b32 s1, 0xff800000
	s_nop 0
	v_addc_co_u32_e32 v81, vcc, 0, v123, vcc
	global_load_dwordx2 v[128:129], v[80:81], off offset:8
	v_add_co_u32_e32 v80, vcc, 0x1b902000, v122
	s_nop 1
	v_addc_co_u32_e32 v81, vcc, 0, v123, vcc
	global_load_dwordx2 v[144:145], v[80:81], off offset:8
	ds_read_b128 v[80:83], v139 offset:18432
	ds_read_b128 v[84:87], v140 offset:18432
	s_waitcnt lgkmcnt(1)
	v_mfma_f32_16x16x32_f16 v[88:91], v[80:83], v[0:3], 0
	v_mfma_f32_16x16x32_f16 v[80:83], v[80:83], v[4:7], 0
	s_waitcnt lgkmcnt(0)
	v_mfma_f32_16x16x32_f16 v[88:91], v[84:87], v[8:11], v[88:91]
	v_mfma_f32_16x16x32_f16 v[80:83], v[84:87], v[12:15], v[80:83]
	ds_read_b128 v[84:87], v139 offset:20480
	ds_read_b128 v[92:95], v140 offset:20480
	s_waitcnt lgkmcnt(1)
	v_mfma_f32_16x16x32_f16 v[96:99], v[84:87], v[0:3], 0
	v_mfma_f32_16x16x32_f16 v[84:87], v[84:87], v[4:7], 0
	s_waitcnt lgkmcnt(0)
	v_mfma_f32_16x16x32_f16 v[96:99], v[92:95], v[8:11], v[96:99]
	v_mfma_f32_16x16x32_f16 v[84:87], v[92:95], v[12:15], v[84:87]
	ds_read_b128 v[92:95], v139 offset:22528
	ds_read_b128 v[100:103], v140 offset:22528
	s_waitcnt lgkmcnt(1)
	v_mfma_f32_16x16x32_f16 v[120:123], v[92:95], v[0:3], 0
	v_mfma_f32_16x16x32_f16 v[92:95], v[92:95], v[4:7], 0
	s_waitcnt lgkmcnt(0)
	v_mfma_f32_16x16x32_f16 v[120:123], v[100:103], v[8:11], v[120:123]
	v_mfma_f32_16x16x32_f16 v[92:95], v[100:103], v[12:15], v[92:95]
	ds_read_b128 v[100:103], v139 offset:24576
	ds_read_b128 v[124:127], v140 offset:24576
	s_waitcnt lgkmcnt(1)
	v_mfma_f32_16x16x32_f16 v[154:157], v[100:103], v[0:3], 0
	v_mfma_f32_16x16x32_f16 v[100:103], v[100:103], v[4:7], 0
	s_waitcnt lgkmcnt(0)
	v_mfma_f32_16x16x32_f16 v[154:157], v[124:127], v[8:11], v[154:157]
	v_mfma_f32_16x16x32_f16 v[100:103], v[124:127], v[12:15], v[100:103]
	s_waitcnt vmcnt(1)
	v_lshrrev_b32_e32 v124, v132, v128
	v_bfe_i32 v126, v124, 0, 1
	v_bfi_b32 v88, v126, v88, v187
	s_waitcnt vmcnt(0)
	v_lshrrev_b32_e32 v125, v132, v144
	v_bfe_i32 v126, v125, 0, 1
	v_bfi_b32 v80, v126, v80, v187
	v_bfe_i32 v126, v124, 1, 1
	v_bfi_b32 v89, v126, v89, v187
	v_bfe_i32 v126, v125, 1, 1
	v_bfi_b32 v81, v126, v81, v187
	v_bfe_i32 v126, v124, 2, 1
	v_bfe_i32 v124, v124, 3, 1
	v_bfi_b32 v90, v126, v90, v187
	v_bfe_i32 v126, v125, 2, 1
	v_bfi_b32 v82, v126, v82, v187
	v_bfi_b32 v91, v124, v91, v187
	v_bfe_i32 v124, v125, 3, 1
	v_lshrrev_b32_e32 v125, v138, v144
	v_bfi_b32 v83, v124, v83, v187
	v_lshrrev_b32_e32 v124, v138, v128
	v_bfe_i32 v126, v124, 0, 1
	v_bfi_b32 v96, v126, v96, v187
	v_bfe_i32 v126, v125, 0, 1
	v_bfi_b32 v127, v126, v84, v187
	v_bfe_i32 v84, v124, 1, 1
	v_bfi_b32 v97, v84, v97, v187
	v_bfe_i32 v84, v125, 1, 1
	v_bfi_b32 v147, v84, v85, v187
	v_bfe_i32 v84, v124, 2, 1
	v_bfi_b32 v85, v84, v98, v187
	v_bfe_i32 v84, v125, 2, 1
	v_bfi_b32 v98, v84, v86, v187
	v_bfe_i32 v84, v124, 3, 1
	v_bfi_b32 v99, v84, v99, v187
	v_bfe_i32 v84, v125, 3, 1
	v_lshrrev_b32_e32 v86, v132, v145
	v_bfi_b32 v125, v84, v87, v187
	v_lshrrev_b32_e32 v84, v132, v129
	v_and_b32_e32 v87, 1, v84
	v_cmp_eq_u32_e32 vcc, 1, v87
	s_nop 1
	v_cndmask_b32_e32 v87, v187, v120, vcc
	v_bfe_i32 v120, v86, 0, 1
	v_bfi_b32 v92, v120, v92, v187
	v_and_b32_e32 v120, 2, v84
	v_cmp_ne_u32_e32 vcc, 0, v120
	s_nop 1
	v_cndmask_b32_e32 v120, v187, v121, vcc
	v_bfe_i32 v121, v86, 1, 1
	v_bfi_b32 v93, v121, v93, v187
	v_and_b32_e32 v121, 4, v84
	v_bfe_i32 v84, v84, 3, 1
	v_cmp_ne_u32_e32 vcc, 0, v121
	s_nop 1
	v_cndmask_b32_e32 v121, v187, v122, vcc
	v_bfe_i32 v122, v86, 2, 1
	v_bfi_b32 v94, v122, v94, v187
	v_bfi_b32 v122, v84, v123, v187
	v_bfe_i32 v84, v86, 3, 1
	v_lshrrev_b32_e32 v86, v138, v145
	v_bfi_b32 v95, v84, v95, v187
	v_lshrrev_b32_e32 v84, v138, v129
	v_and_b32_e32 v123, 1, v84
	v_cmp_eq_u32_e32 vcc, 1, v123
	v_bfe_i32 v124, v86, 0, 1
	s_nop 0
	v_cndmask_b32_e32 v123, v187, v154, vcc
	v_bfi_b32 v129, v124, v100, v187
	v_bfe_i32 v124, v86, 1, 1
	v_and_b32_e32 v100, 2, v84
	v_cmp_ne_u32_e32 vcc, 0, v100
	s_nop 1
	v_cndmask_b32_e32 v100, v187, v155, vcc
	v_bfi_b32 v101, v124, v101, v187
	v_bfe_i32 v124, v84, 2, 1
	v_bfe_i32 v84, v84, 3, 1
	v_bfi_b32 v128, v124, v156, v187
	v_bfe_i32 v124, v86, 2, 1
	v_bfi_b32 v102, v124, v102, v187
	v_bfi_b32 v130, v84, v157, v187
	v_bfe_i32 v84, v86, 3, 1
	v_bfi_b32 v103, v84, v103, v187
	v_max_f32_e32 v84, v90, v91
	v_max_f32_e32 v86, v85, v99
	v_max_f32_e32 v124, v87, v120
	v_max_f32_e32 v126, v121, v122
	v_max_f32_e32 v144, v128, v130
	v_max3_f32 v144, v123, v100, v144
	v_max3_f32 v84, v88, v89, v84
	v_max3_f32 v86, v96, v97, v86
	v_max3_f32 v124, v124, v126, v144
	v_max3_f32 v84, v84, v86, v124
	v_mov_b32_e32 v86, v84
	s_waitcnt lgkmcnt(0)
	s_nop 1
	v_permlane16_swap_b32_e32 v84, v86
	v_max_f32_e32 v84, v84, v86
	v_mov_b32_e32 v86, v84
	s_waitcnt lgkmcnt(0)
	s_nop 1
	v_permlane32_swap_b32_e32 v84, v86
	v_max3_f32 v144, v131, v84, v86
	v_cmp_neq_f32_e32 vcc, s1, v144
	s_nop 1
	v_cndmask_b32_e32 v145, 0, v144, vcc
	v_sub_f32_e32 v84, v88, v145
	v_sub_f32_e32 v88, v90, v145
	v_exp_f32_e32 v162, v88
	v_sub_f32_e32 v88, v91, v145
	v_sub_f32_e32 v85, v85, v145
	v_exp_f32_e32 v164, v88
	v_sub_f32_e32 v88, v96, v145
	v_exp_f32_e32 v170, v85
	v_sub_f32_e32 v85, v99, v145
	v_exp_f32_e32 v166, v88
	v_sub_f32_e32 v88, v97, v145
	v_exp_f32_e32 v190, v85
	v_sub_f32_e32 v85, v87, v145
	v_exp_f32_e32 v168, v88
	v_exp_f32_e32 v88, v85
	v_sub_f32_e32 v85, v120, v145
	v_exp_f32_e32 v90, v85
	v_sub_f32_e32 v85, v121, v145
	v_exp_f32_e32 v120, v85
	v_sub_f32_e32 v85, v122, v145
	v_exp_f32_e32 v122, v85
	v_sub_f32_e32 v85, v123, v145
	v_exp_f32_e32 v124, v85
	v_sub_f32_e32 v85, v100, v145
	v_exp_f32_e32 v126, v85
	v_sub_f32_e32 v85, v128, v145
	v_exp_f32_e32 v128, v85
	v_sub_f32_e32 v85, v130, v145
	v_exp_f32_e32 v130, v85
	v_sub_f32_e32 v85, v131, v145
	v_exp_f32_e32 v100, v85
	v_sub_f32_e32 v86, v89, v145
	v_max_f32_e32 v85, v82, v83
	v_max_f32_e32 v87, v98, v125
	v_max_f32_e32 v89, v92, v93
	v_max_f32_e32 v91, v94, v95
	v_max_f32_e32 v96, v102, v103
	v_max3_f32 v96, v129, v101, v96
	v_max3_f32 v85, v80, v81, v85
	v_max3_f32 v87, v127, v147, v87
	v_max3_f32 v89, v89, v91, v96
	v_max3_f32 v85, v85, v87, v89
	v_mov_b32_e32 v87, v85
	v_exp_f32_e32 v84, v84
	v_exp_f32_e32 v86, v86
	v_pk_mul_f32 v[70:71], v[70:71], v[100:101] op_sel_hi:[1,0]
	v_pk_mul_f32 v[68:69], v[68:69], v[100:101] op_sel_hi:[1,0]
	s_waitcnt lgkmcnt(0)
; DI void gload2(R2& r, const bf16_t* gsrc, size_t gp, int tid) { r.a = ld_chunk(gsrc, gp, tid); r.b = ld_chunk(gsrc, gp, tid + 256); }
; DI void sstoreK2(const R2& r, char* sdst, int tid) { st_chunk_k(sdst, tid, r.a); st_chunk_k(sdst, tid + 256, r.b); }
; DI void sstoreV2(const R2& r, char* sdst, int tid) { st_chunk_v(sdst, tid, r.a); st_chunk_v(sdst, tid + 256, r.b); }
; DI void attn_C2x(const Params& P, int b, int head, int qp, char* smem, bf16_t* ybase, size_t ypitch) {
;     ...
;   for (int n = 0; n <= nlast; n += 2) {
;     if (n + 2 <= nlast) { gload2(rk0, kbase + (size_t)(n + 2) * 64 * PW, PW, tid); gload2(rv0, vbase + (n + 2) * 64, SEQ, tid); }
;     C2X_COMPUTE(n, smem)
;     sstoreK2(rk1, smem + STAGE, tid); sstoreV2(rv1, smem + STAGE + 9216, tid);
;     __syncthreads();
;     if (n + 3 <= nlast) { gload2(rk1, kbase + (size_t)(n + 3) * 64 * PW, PW, tid); gload2(rv1, vbase + (n + 3) * 64, SEQ, tid); }
;     C2X_COMPUTE(n + 1, smem + STAGE)
;     if (n + 2 <= nlast) { sstoreK2(rk0, smem, tid); sstoreV2(rv0, smem + 9216, tid); }
;     __syncthreads();
	s_nop 1
	v_permlane16_swap_b32_e32 v85, v87
	v_max_f32_e32 v85, v85, v87
	v_mov_b32_e32 v87, v85
	v_pk_mul_f32 v[156:157], v[54:55], v[100:101] op_sel_hi:[1,0]
	v_pk_mul_f32 v[154:155], v[52:53], v[100:101] op_sel_hi:[1,0]
	s_waitcnt lgkmcnt(0)
	s_nop 1
	v_permlane32_swap_b32_e32 v85, v87
	v_max3_f32 v145, v146, v85, v87
	v_cmp_neq_f32_e32 vcc, s1, v145
	s_nop 1
	v_cndmask_b32_e32 v96, 0, v145, vcc
	v_sub_f32_e32 v80, v80, v96
	v_exp_f32_e32 v85, v80
	v_sub_f32_e32 v80, v81, v96
	v_exp_f32_e32 v87, v80
	v_sub_f32_e32 v80, v82, v96
	v_exp_f32_e32 v163, v80
	v_sub_f32_e32 v80, v83, v96
	v_exp_f32_e32 v165, v80
	v_sub_f32_e32 v80, v127, v96
	v_exp_f32_e32 v167, v80
	v_sub_f32_e32 v80, v147, v96
	v_exp_f32_e32 v169, v80
	v_sub_f32_e32 v80, v98, v96
	v_exp_f32_e32 v171, v80
	v_sub_f32_e32 v80, v125, v96
	v_exp_f32_e32 v191, v80
	v_sub_f32_e32 v80, v92, v96
	v_exp_f32_e32 v89, v80
	v_sub_f32_e32 v80, v93, v96
	v_exp_f32_e32 v91, v80
	v_sub_f32_e32 v80, v94, v96
	v_exp_f32_e32 v121, v80
	v_sub_f32_e32 v80, v95, v96
	v_exp_f32_e32 v123, v80
	v_sub_f32_e32 v80, v129, v96
	v_exp_f32_e32 v125, v80
	v_sub_f32_e32 v80, v101, v96
	v_exp_f32_e32 v127, v80
	v_sub_f32_e32 v80, v102, v96
	v_exp_f32_e32 v129, v80
	v_sub_f32_e32 v80, v103, v96
	v_exp_f32_e32 v131, v80
	v_sub_f32_e32 v80, v146, v96
	v_exp_f32_e32 v102, v80
	v_pk_mul_f32 v[82:83], v[62:63], v[100:101] op_sel_hi:[1,0]
	v_pk_mul_f32 v[80:81], v[60:61], v[100:101] op_sel_hi:[1,0]
	v_cvt_pk_f16_f32 v60, v84, v86
	v_pk_mul_f32 v[160:161], v[50:51], v[102:103] op_sel_hi:[1,0]
	v_pk_mul_f32 v[158:159], v[48:49], v[102:103] op_sel_hi:[1,0]
	v_pk_mul_f32 v[50:51], v[74:75], v[100:101] op_sel_hi:[1,0]
	v_pk_mul_f32 v[48:49], v[72:73], v[100:101] op_sel_hi:[1,0]
	ds_read_b128 v[72:75], v139 offset:29696
	v_pk_mul_f32 v[92:93], v[56:57], v[102:103] op_sel_hi:[1,0]
	v_pk_add_f32 v[56:57], v[84:85], 0 op_sel_hi:[1,0]
	v_pk_mul_f32 v[98:99], v[66:67], v[102:103] op_sel_hi:[1,0]
	v_pk_add_f32 v[56:57], v[86:87], v[56:57]
	v_pk_mul_f32 v[96:97], v[64:65], v[102:103] op_sel_hi:[1,0]
	v_pk_add_f32 v[56:57], v[162:163], v[56:57]
	v_cvt_pk_f16_f32 v61, v162, v164
	v_pk_add_f32 v[56:57], v[164:165], v[56:57]
	v_cvt_pk_f16_f32 v62, v166, v168
	v_pk_add_f32 v[56:57], v[166:167], v[56:57]
	v_cvt_pk_f16_f32 v63, v170, v190
	v_pk_add_f32 v[56:57], v[168:169], v[56:57]
	v_cvt_pk_f16_f32 v84, v85, v87
	v_pk_add_f32 v[56:57], v[170:171], v[56:57]
	v_cvt_pk_f16_f32 v85, v163, v165
	v_cvt_pk_f16_f32 v86, v167, v169
	v_cvt_pk_f16_f32 v87, v171, v191
	ds_read_b128 v[64:67], v139 offset:27648
	v_pk_add_f32 v[56:57], v[190:191], v[56:57]
	s_waitcnt lgkmcnt(1)
	v_mfma_f32_16x16x32_f16 v[68:71], v[72:75], v[60:63], v[68:71]
	v_add_f32_e64 v56, v88, v56
	v_add_f32_e64 v57, v89, v57
	v_pk_mul_f32 v[94:95], v[58:59], v[102:103] op_sel_hi:[1,0]
	v_pk_add_f32 v[56:57], v[90:91], v[56:57]
	v_mfma_f32_16x16x32_f16 v[72:75], v[72:75], v[84:87], v[96:99]
	v_add_f32_e64 v56, v120, v56
	v_add_f32_e64 v57, v121, v57
	v_pk_mul_f32 v[54:55], v[78:79], v[102:103] op_sel_hi:[1,0]
	v_pk_add_f32 v[56:57], v[122:123], v[56:57]
	ds_read_b128 v[96:99], v139 offset:33792
	v_pk_add_f32 v[56:57], v[124:125], v[56:57]
	v_pk_mul_f32 v[52:53], v[76:77], v[102:103] op_sel_hi:[1,0]
	v_pk_add_f32 v[56:57], v[126:127], v[56:57]
	v_mov_b32_e32 v101, v102
	v_pk_add_f32 v[56:57], v[128:129], v[56:57]
	v_mov_b32_e32 v146, v145
	v_pk_add_f32 v[102:103], v[130:131], v[56:57]
	s_waitcnt lgkmcnt(1)
	v_mfma_f32_16x16x32_f16 v[56:59], v[64:67], v[60:63], v[80:83]
	v_fma_f32 v118, v118, v100, v102
	v_fma_f32 v119, v119, v101, v103
	s_nop 0
	ds_read_b128 v[80:83], v139 offset:31744
	v_mfma_f32_16x16x32_f16 v[64:67], v[64:67], v[84:87], v[92:95]
	s_waitcnt lgkmcnt(1)
	v_mfma_f32_16x16x32_f16 v[92:95], v[96:99], v[60:63], v[48:51]
	s_nop 2
	ds_read_b128 v[48:51], v140 offset:27648
	s_waitcnt lgkmcnt(1)
	v_mfma_f32_16x16x32_f16 v[76:79], v[80:83], v[60:63], v[154:157]
	v_mfma_f32_16x16x32_f16 v[80:83], v[80:83], v[84:87], v[158:161]
	v_mfma_f32_16x16x32_f16 v[84:87], v[96:99], v[84:87], v[52:55]
	v_cvt_pk_f16_f32 v96, v88, v90
	v_cvt_pk_f16_f32 v97, v120, v122
	v_cvt_pk_f16_f32 v98, v124, v126
	v_cvt_pk_f16_f32 v99, v128, v130
	v_cvt_pk_f16_f32 v88, v89, v91
	v_cvt_pk_f16_f32 v89, v121, v123
	v_cvt_pk_f16_f32 v90, v125, v127
	v_cvt_pk_f16_f32 v91, v129, v131
	s_waitcnt lgkmcnt(0)
	v_mfma_f32_16x16x32_f16 v[60:63], v[48:51], v[96:99], v[56:59]
	v_mov_b32_e32 v131, v144
	v_mfma_f32_16x16x32_f16 v[56:59], v[48:51], v[88:91], v[64:67]
	ds_read_b128 v[48:51], v140 offset:29696
	s_waitcnt lgkmcnt(0)
	v_mfma_f32_16x16x32_f16 v[68:71], v[48:51], v[96:99], v[68:71]
	v_mfma_f32_16x16x32_f16 v[64:67], v[48:51], v[88:91], v[72:75]
	ds_read_b128 v[48:51], v140 offset:31744
	s_waitcnt lgkmcnt(0)
	v_mfma_f32_16x16x32_f16 v[52:55], v[48:51], v[96:99], v[76:79]
	s_nop 2
	ds_read_b128 v[76:79], v140 offset:33792
	v_mfma_f32_16x16x32_f16 v[48:51], v[48:51], v[88:91], v[80:83]
	s_waitcnt lgkmcnt(0)
	v_mfma_f32_16x16x32_f16 v[72:75], v[76:79], v[96:99], v[92:95]
	v_mfma_f32_16x16x32_f16 v[76:79], v[76:79], v[88:91], v[84:87]
	s_or_b64 exec, exec, s[12:13]
	s_andn2_b64 vcc, exec, s[10:11]
	s_cbranch_vccnz .LBB0_1076
